# v104 + DSA B1: the first iteration's second tile group (16 loads) is issued with the prologue loads, wait relaxed from vmcnt(0) to vmcnt(16)
# baseline (speedup 1.0000x reference)
; __device__ __forceinline__ float bf2f(u16 b) { return __uint_as_float(((unsigned)b) << 16); }
;     ...
;       { const u16* qp = prow + (size_t)(t0 + (c32 >> 2)) * NP + C_QI + (c32 & 3) * 64 + 8 * hi;
; #pragma unroll
;         for (int ks = 0; ks < 4; ++ks) qa[ks] = *(const bf16x8*)(qp + ks * 16); }
;       float wv[16];
; #pragma unroll
;       for (int r = 0; r < 16; ++r) wv[r] = 0.5f * bf2f(prow[(size_t)(t0 + 2 * (r >> 2) + hi) * NP + C_WI + (r & 3)]);
; #pragma unroll
;       for (int r = 0; r < 16; ++r) wv[r] *= 0.125f;
;       auto ldb = [&](bf16x8 (&kk)[4][4], int i0) {
; #pragma unroll
;           for (int j = 0; j < 4; ++j) { int T = wid + 8 * (i0 + j); T = T < ntile32 ? T : ntile32 - 1; const u16* kp = p.kiP + (((size_t)bl * 128 + T) * 256 + lane) * 8;
; #pragma unroll
;               for (int ks = 0; ks < 4; ++ks) kk[j][ks] = *(const bf16x8*)(kp + ks * 512); } };
;     ...
;       if (sm & 1) {
;           const int nT = (ntile32 - wid + 7) >> 3;
;           bf16x8 ka[4][4], kc[4][4];
;           ldb(ka, 0);
;           for (int i0 = 0; i0 < nT; i0 += 8) { ldb(kc, i0 + 4); comp(ka, i0); ldb(ka, i0 + 8); comp(kc, i0 + 4); }
.LBB0_178:
	s_and_b64 vcc, exec, s[38:39]
	s_cbranch_vccz .LBB0_970
	s_lshl_b32 s0, s58, 1
	s_and_b32 s37, s58, 3
	s_and_b32 s0, s0, 0x1ff8
	v_mov_b32_e32 v174, v198
	s_sub_i32 s30, 0x11f8, s0
	s_sub_i32 s0, 0x1218, s0
	s_mul_i32 s1, s37, 0x5800000
	s_add_u32 s54, s14, s1
	v_readfirstlane_b32 s59, v174
	s_addc_u32 s55, s15, 0
	s_ashr_i32 s64, s59, 6
	s_lshr_b32 s0, s0, 5
	s_sub_i32 s1, s0, s64
	s_add_i32 s1, s1, 7
	s_ashr_i32 s1, s1, 3
	s_cmp_lt_i32 s1, 1
	v_and_b32_e32 v163, 63, v174
	s_cbranch_scc1 .LBB0_198
	v_lshrrev_b32_e32 v14, 5, v163
	v_or_b32_e32 v0, s30, v14
	v_mul_i32_i24_e32 v0, 0x5800, v0
	v_lshl_add_u64 v[2:3], s[54:55], 0, v[0:1]
	v_add_co_u32_e32 v4, vcc, 0x1000, v2
	s_mov_b32 s20, 0xc000
	s_nop 0
	v_addc_co_u32_e32 v5, vcc, 0, v3, vcc
	v_bfe_u32 v0, v174, 2, 3
	v_add_co_u32_e32 v6, vcc, s20, v2
	v_or_b32_e32 v0, s30, v0
	s_nop 0
	v_addc_co_u32_e32 v7, vcc, 0, v3, vcc
	s_mov_b32 s20, 0x17000
	v_mul_i32_i24_e32 v0, 0x2c00, v0
	v_add_co_u32_e32 v8, vcc, s20, v2
	v_lshl_add_u64 v[10:11], v[0:1], 1, s[54:55]
	v_lshlrev_b32_e32 v0, 7, v163
	v_addc_co_u32_e32 v9, vcc, 0, v3, vcc
	s_mov_b32 s20, 0x22000
	v_and_b32_e32 v0, 0x180, v0
	v_add_co_u32_e32 v2, vcc, s20, v2
	v_lshl_add_u64 v[10:11], v[10:11], 0, v[0:1]
	v_lshlrev_b32_e32 v0, 4, v14
	v_addc_co_u32_e32 v3, vcc, 0, v3, vcc
	v_lshl_add_u64 v[10:11], v[10:11], 0, v[0:1]
	s_mov_b64 s[22:23], 0x1100
	s_movk_i32 s21, 0x1000
	s_add_i32 s20, s0, -1
	v_lshl_add_u64 v[12:13], v[10:11], 0, s[22:23]
	v_add_co_u32_e32 v10, vcc, s21, v10
	s_add_i32 s21, s64, 24
	s_min_i32 s22, s21, s20
	s_ashr_i32 s23, s22, 31
	s_lshl_b32 s24, s37, 15
	s_lshl_b64 s[22:23], s[22:23], 8
	s_add_u32 s21, s22, s24
	global_load_dwordx2 v[4:5], v[4:5], off offset:896
	s_nop 0
	global_load_dwordx2 v[6:7], v[6:7], off offset:896
	s_nop 0
	global_load_dwordx2 v[8:9], v[8:9], off offset:896
	s_nop 0
	global_load_dwordx2 v[2:3], v[2:3], off offset:896
	s_nop 0
	global_load_dwordx4 v[18:21], v[12:13], off offset:64
	global_load_dwordx4 v[22:25], v[12:13], off offset:32
	v_addc_co_u32_e32 v11, vcc, 0, v11, vcc
	global_load_dwordx4 v[26:29], v[12:13], off offset:96
	global_load_dwordx4 v[30:33], v[10:11], off offset:256
	s_addc_u32 s22, s23, 0
	v_or_b32_e32 v10, s21, v163
	s_add_i32 s21, s64, 16
	v_mov_b32_e32 v11, s22
	s_min_i32 s22, s21, s20
	v_readlane_b32 s40, v251, 1
	s_ashr_i32 s23, s22, 31
	v_readlane_b32 s41, v251, 2
	s_lshl_b64 s[22:23], s[22:23], 8
	s_add_u32 s21, s22, s24
	v_lshl_add_u64 v[10:11], v[10:11], 4, s[40:41]
	global_load_dwordx4 v[34:37], v[10:11], off offset:3072
	global_load_dwordx4 v[38:41], v[10:11], off offset:2048
	global_load_dwordx4 v[42:45], v[10:11], off offset:1024
	global_load_dwordx4 v[46:49], v[10:11], off
	s_addc_u32 s22, s23, 0
	v_or_b32_e32 v10, s21, v163
	s_add_i32 s21, s64, 8
	v_mov_b32_e32 v11, s22
	s_min_i32 s22, s21, s20
	s_ashr_i32 s23, s22, 31
	s_lshl_b64 s[22:23], s[22:23], 8
	s_add_u32 s21, s22, s24
	v_lshl_add_u64 v[10:11], v[10:11], 4, s[40:41]
	s_addc_u32 s22, s23, 0
	global_load_dwordx4 v[50:53], v[10:11], off offset:3072
	global_load_dwordx4 v[54:57], v[10:11], off offset:2048
	global_load_dwordx4 v[58:61], v[10:11], off offset:1024
	global_load_dwordx4 v[62:65], v[10:11], off
	v_mov_b32_e32 v11, s22
	s_min_i32 s22, s64, s20
	s_ashr_i32 s23, s22, 31
	s_lshl_b64 s[22:23], s[22:23], 8
	v_or_b32_e32 v10, s21, v163
	s_add_u32 s21, s22, s24
	v_lshl_add_u64 v[10:11], v[10:11], 4, s[40:41]
	s_addc_u32 s22, s23, 0
	global_load_dwordx4 v[82:85], v[10:11], off offset:3072
	global_load_dwordx4 v[86:89], v[10:11], off offset:2048
	global_load_dwordx4 v[90:93], v[10:11], off offset:1024
	global_load_dwordx4 v[94:97], v[10:11], off
	v_or_b32_e32 v10, s21, v163
	v_mov_b32_e32 v11, s22
	v_lshl_add_u64 v[10:11], v[10:11], 4, s[40:41]
	global_load_dwordx4 v[114:117], v[10:11], off offset:3072
	global_load_dwordx4 v[118:121], v[10:11], off offset:2048
	global_load_dwordx4 v[122:125], v[10:11], off offset:1024
	global_load_dwordx4 v[126:129], v[10:11], off
	s_lshl_b32 s23, s64, 7
	s_mov_b32 s21, 0
	s_add_i32 s22, s64, 0x58
	v_readlane_b32 s42, v251, 3
	v_readlane_b32 s43, v251, 4
	v_readlane_b32 s44, v251, 5
	v_readlane_b32 s45, v251, 6
	v_readlane_b32 s46, v251, 7
	v_readlane_b32 s47, v251, 8
	v_or_b32_e32 v0, s24, v163
	v_lshlrev_b32_e32 v0, 4, v0
	v_lshl_add_u64 v[172:173], s[40:41], 0, v[0:1]
	s_sub_i32 s28, s22, 56
	s_min_i32 s28, s28, s20
	s_ashr_i32 s29, s28, 31
	s_lshl_b64 s[28:29], s[28:29], 12
	v_lshl_add_u64 v[224:225], v[172:173], 0, s[28:29]
	global_load_dwordx4 v[158:161], v[224:225], off
	global_load_dwordx4 v[154:157], v[224:225], off offset:1024
	global_load_dwordx4 v[150:153], v[224:225], off offset:2048
	global_load_dwordx4 v[146:149], v[224:225], off offset:3072
	s_sub_i32 s28, s22, 48
	s_min_i32 s28, s28, s20
	s_ashr_i32 s29, s28, 31
	s_lshl_b64 s[28:29], s[28:29], 12
	v_lshl_add_u64 v[224:225], v[172:173], 0, s[28:29]
	global_load_dwordx4 v[142:145], v[224:225], off
	global_load_dwordx4 v[138:141], v[224:225], off offset:1024
	global_load_dwordx4 v[134:137], v[224:225], off offset:2048
	global_load_dwordx4 v[130:133], v[224:225], off offset:3072
	s_sub_i32 s28, s22, 40
	s_min_i32 s28, s28, s20
	s_ashr_i32 s29, s28, 31
	s_lshl_b64 s[28:29], s[28:29], 12
	v_lshl_add_u64 v[224:225], v[172:173], 0, s[28:29]
	global_load_dwordx4 v[110:113], v[224:225], off
	global_load_dwordx4 v[106:109], v[224:225], off offset:1024
	global_load_dwordx4 v[102:105], v[224:225], off offset:2048
	global_load_dwordx4 v[98:101], v[224:225], off offset:3072
	s_sub_i32 s28, s22, 32
	s_min_i32 s28, s28, s20
	s_ashr_i32 s29, s28, 31
	s_lshl_b64 s[28:29], s[28:29], 12
	v_lshl_add_u64 v[224:225], v[172:173], 0, s[28:29]
	global_load_dwordx4 v[78:81], v[224:225], off
	global_load_dwordx4 v[74:77], v[224:225], off offset:1024
	global_load_dwordx4 v[70:73], v[224:225], off offset:2048
	global_load_dwordx4 v[66:69], v[224:225], off offset:3072
	s_waitcnt vmcnt(16)
; __device__ __forceinline__ float bf2f(u16 b) { return __uint_as_float(((unsigned)b) << 16); }
;     ...
;       float wv[16];
; #pragma unroll
;       for (int r = 0; r < 16; ++r) wv[r] = 0.5f * bf2f(prow[(size_t)(t0 + 2 * (r >> 2) + hi) * NP + C_WI + (r & 3)]);
; #pragma unroll
;       for (int r = 0; r < 16; ++r) wv[r] *= 0.125f;
	v_lshlrev_b32_e32 v0, 16, v4
	v_mul_f32_e32 v0, 0.5, v0
	v_mul_f32_e32 v175, 0x3e000000, v0
	s_waitcnt vmcnt(20)
	v_lshlrev_b32_e32 v16, 16, v2
	v_and_b32_e32 v2, 0xffff0000, v2
	v_or_b32_e32 v0, s24, v163
	v_mul_f32_e32 v2, 0.5, v2
	v_lshlrev_b32_e32 v0, 4, v0
	v_and_b32_e32 v4, 0xffff0000, v4
	v_lshlrev_b32_e32 v10, 16, v5
	v_and_b32_e32 v5, 0xffff0000, v5
	v_lshlrev_b32_e32 v11, 16, v6
	v_and_b32_e32 v6, 0xffff0000, v6
	v_lshlrev_b32_e32 v12, 16, v7
	v_and_b32_e32 v7, 0xffff0000, v7
	v_lshlrev_b32_e32 v13, 16, v8
	v_and_b32_e32 v8, 0xffff0000, v8
	v_lshlrev_b32_e32 v15, 16, v9
	v_and_b32_e32 v9, 0xffff0000, v9
	v_lshlrev_b32_e32 v17, 16, v3
	v_and_b32_e32 v3, 0xffff0000, v3
	v_mul_f32_e32 v189, 0x3e000000, v2
	v_and_b32_e32 v2, 31, v174
	v_lshl_add_u64 v[172:173], s[40:41], 0, v[0:1]
	v_lshl_add_u32 v0, v14, 14, s23
	v_mul_f32_e32 v4, 0.5, v4
	v_mul_f32_e32 v10, 0.5, v10
	v_mul_f32_e32 v5, 0.5, v5
	v_mul_f32_e32 v11, 0.5, v11
	v_mul_f32_e32 v6, 0.5, v6
	v_mul_f32_e32 v12, 0.5, v12
	v_mul_f32_e32 v7, 0.5, v7
	v_mul_f32_e32 v13, 0.5, v13
	v_mul_f32_e32 v8, 0.5, v8
	v_mul_f32_e32 v15, 0.5, v15
	v_mul_f32_e32 v9, 0.5, v9
	v_mul_f32_e32 v16, 0.5, v16
	v_mul_f32_e32 v17, 0.5, v17
	v_mul_f32_e32 v3, 0.5, v3
	v_lshl_or_b32 v0, v2, 2, v0
	v_mul_f32_e32 v176, 0x3e000000, v4
	v_mul_f32_e32 v177, 0x3e000000, v10
	v_mul_f32_e32 v178, 0x3e000000, v5
	v_mul_f32_e32 v179, 0x3e000000, v11
	v_mul_f32_e32 v181, 0x3e000000, v6
	v_mul_f32_e32 v182, 0x3e000000, v12
	v_mul_f32_e32 v183, 0x3e000000, v7
	v_mul_f32_e32 v184, 0x3e000000, v13
	v_mul_f32_e32 v185, 0x3e000000, v8
	v_mul_f32_e32 v186, 0x3e000000, v15
	v_mul_f32_e32 v187, 0x3e000000, v9
	v_mul_f32_e32 v188, 0x3e000000, v16
	v_mul_f32_e32 v190, 0x3e000000, v17
	v_mul_f32_e32 v191, 0x3e000000, v3
	v_add_u32_e32 v0, 0, v0
	s_sub_i32 s26, s22, 56
	s_sub_i32 s25, s22, 48
	s_sub_i32 s24, s22, 40
	s_sub_i32 s23, s22, 32
	s_branch .Lb1_first

;     ...
;       auto comp = [&](const bf16x8 (&kk)[4][4], int i0) {
; #pragma unroll
;           for (int j = 0; j < 4; ++j) {
;               const int T = wid + 8 * (i0 + j);
;               if (T < ntile32) {
;     ...
;           for (int i0 = 0; i0 < nT; i0 += 8) { ldb(kc, i0 + 4); comp(ka, i0); ldb(ka, i0 + 8); comp(kc, i0 + 4); }
.Lb1_first:
	s_add_i32 s27, s22, 0xffffffa8
	s_cmp_ge_i32 s27, s0
	s_cbranch_scc0 .LBB0_191
	s_add_i32 s27, s22, 0xffffffb0
	s_cmp_ge_i32 s27, s0
	s_cbranch_scc0 .LBB0_192
